# diff-attn block epilogue: O/O2 tiles transposed through wave-private LDS scratch and written with 16 full-width 16-byte stores per wave instead of 128 half-masked 4-byte stores
# speedup vs baseline: 1.0076x; 1.0076x over previous
; __device__ __forceinline__ unsigned cvtpk(float lo, float hi) { unsigned r; asm volatile("v_cvt_pk_bf16_f32 %0, %1, %2" : "=v"(r) : "v"(lo), "v"(hi)); return r; }
; __device__ __forceinline__ float xor1_(float v) { return __int_as_float(__builtin_amdgcn_update_dpp(0, __float_as_int(v), 0xB1, 0xf, 0xf, false)); }
; __device__ __forceinline__ int crow(int r, int hi) { return (r & 3) + 8 * (r >> 2) + 4 * hi; }
; __device__ __forceinline__ void attn_block3(const BlockRef& cur, char* lds, const int wid) {
;     ...
;     if (hi == 0) li_l[r32] = l_reg; asm volatile("s_waitcnt lgkmcnt(0)" ::: "memory");
; #pragma unroll
;     for (int r = 0; r < 16; ++r) { const int orow = crow(r, hi); const float rli = __builtin_amdgcn_rcpf(li_l[orow]);
;         const size_t ro = (size_t)(wid * QBLK + orow) * D;
; #pragma unroll
;         for (int d0 = 0; d0 < 4; ++d0) { const float v = o[d0][r] * rli, v2 = o2[d0][r] * rli; const float vn = xor1_(v), vn2 = xor1_(v2);
;             if ((r32 & 1) == 0) { __builtin_nontemporal_store(cvtpk(v, vn), (unsigned*)(cur.O + ro + d0 * 32 + r32)); __builtin_nontemporal_store(cvtpk(v2, vn2), (unsigned*)(cur.O2 + ro + d0 * 32 + r32)); } } }
.LBB0_491:
	s_and_saveexec_b64 s[6:7], s[4:5]
	ds_write_b32 v241, v250
	s_or_b64 exec, exec, s[6:7]
	s_lshl_b32 s4, s44, 15
	s_or_b32 s44, s4, s78
	s_lshl_b64 s[4:5], s[44:45], 1
	s_add_u32 s4, s30, s4
	s_addc_u32 s5, s31, s5
	s_lshl_b32 s20, s39, 8
	s_add_u32 s4, s4, s20
	s_addc_u32 s5, s5, 0
	s_add_u32 s6, s4, 0x400000
	s_addc_u32 s7, s5, 0
	s_mul_i32 s20, s39, 272
	v_lshlrev_b32_e32 v2, 1, v238
	v_mul_u32_u24_e32 v3, 272, v236
	v_add3_u32 v2, v2, v3, s20
	v_lshrrev_b32_e32 v3, 4, v239
	v_mul_u32_u24_e32 v3, 272, v3
	v_and_b32_e32 v4, 15, v239
	v_lshlrev_b32_e32 v4, 4, v4
	v_add3_u32 v4, v4, v3, s20
	v_lshlrev_b32_e32 v3, 4, v239
	v_add_u32_e32 v5, 0x1000, v3
	s_waitcnt lgkmcnt(0)
	ds_read_b32 v208, v237
	ds_read_b32 v209, v237 offset:4
	ds_read_b32 v210, v237 offset:8
	ds_read_b32 v211, v237 offset:12
	ds_read_b32 v212, v237 offset:32
	ds_read_b32 v213, v237 offset:36
	ds_read_b32 v214, v237 offset:40
	ds_read_b32 v215, v237 offset:44
	ds_read_b32 v216, v237 offset:64
	ds_read_b32 v217, v237 offset:68
	ds_read_b32 v218, v237 offset:72
	ds_read_b32 v219, v237 offset:76
	ds_read_b32 v220, v237 offset:96
	ds_read_b32 v221, v237 offset:100
	ds_read_b32 v222, v237 offset:104
	ds_read_b32 v223, v237 offset:108
	s_waitcnt lgkmcnt(0)
	v_rcp_f32_e32 v208, v208
	v_rcp_f32_e32 v209, v209
	v_rcp_f32_e32 v210, v210
	v_rcp_f32_e32 v211, v211
	v_rcp_f32_e32 v212, v212
	v_rcp_f32_e32 v213, v213
	v_rcp_f32_e32 v214, v214
	v_rcp_f32_e32 v215, v215
	v_rcp_f32_e32 v216, v216
	v_rcp_f32_e32 v217, v217
	v_rcp_f32_e32 v218, v218
	v_rcp_f32_e32 v219, v219
	v_rcp_f32_e32 v220, v220
	v_rcp_f32_e32 v221, v221
	v_rcp_f32_e32 v222, v222
	v_rcp_f32_e32 v223, v223
	v_mul_f32_e32 v8, v112, v208
	v_cvt_pk_bf16_f32 v8, v8, v8
	ds_write_b16 v2, v8
	v_mul_f32_e32 v9, v113, v209
	v_cvt_pk_bf16_f32 v9, v9, v9
	ds_write_b16 v2, v9 offset:272
	v_mul_f32_e32 v10, v114, v210
	v_cvt_pk_bf16_f32 v10, v10, v10
	ds_write_b16 v2, v10 offset:544
	v_mul_f32_e32 v11, v115, v211
	v_cvt_pk_bf16_f32 v11, v11, v11
	ds_write_b16 v2, v11 offset:816
	v_mul_f32_e32 v12, v116, v212
	v_cvt_pk_bf16_f32 v12, v12, v12
	ds_write_b16 v2, v12 offset:2176
	v_mul_f32_e32 v13, v117, v213
	v_cvt_pk_bf16_f32 v13, v13, v13
	ds_write_b16 v2, v13 offset:2448
	v_mul_f32_e32 v14, v118, v214
	v_cvt_pk_bf16_f32 v14, v14, v14
	ds_write_b16 v2, v14 offset:2720
	v_mul_f32_e32 v15, v119, v215
	v_cvt_pk_bf16_f32 v15, v15, v15
	ds_write_b16 v2, v15 offset:2992
	v_mul_f32_e32 v8, v120, v216
	v_cvt_pk_bf16_f32 v8, v8, v8
	ds_write_b16 v2, v8 offset:4352
	v_mul_f32_e32 v9, v121, v217
	v_cvt_pk_bf16_f32 v9, v9, v9
	ds_write_b16 v2, v9 offset:4624
	v_mul_f32_e32 v10, v122, v218
	v_cvt_pk_bf16_f32 v10, v10, v10
	ds_write_b16 v2, v10 offset:4896
	v_mul_f32_e32 v11, v123, v219
	v_cvt_pk_bf16_f32 v11, v11, v11
	ds_write_b16 v2, v11 offset:5168
	v_mul_f32_e32 v12, v124, v220
	v_cvt_pk_bf16_f32 v12, v12, v12
	ds_write_b16 v2, v12 offset:6528
	v_mul_f32_e32 v13, v125, v221
	v_cvt_pk_bf16_f32 v13, v13, v13
	ds_write_b16 v2, v13 offset:6800
	v_mul_f32_e32 v14, v126, v222
	v_cvt_pk_bf16_f32 v14, v14, v14
	ds_write_b16 v2, v14 offset:7072
	v_mul_f32_e32 v15, v127, v223
	v_cvt_pk_bf16_f32 v15, v15, v15
	ds_write_b16 v2, v15 offset:7344
	v_mul_f32_e32 v8, v80, v208
	v_cvt_pk_bf16_f32 v8, v8, v8
	ds_write_b16 v2, v8 offset:64
	v_mul_f32_e32 v9, v81, v209
	v_cvt_pk_bf16_f32 v9, v9, v9
	ds_write_b16 v2, v9 offset:336
	v_mul_f32_e32 v10, v82, v210
	v_cvt_pk_bf16_f32 v10, v10, v10
	ds_write_b16 v2, v10 offset:608
	v_mul_f32_e32 v11, v83, v211
	v_cvt_pk_bf16_f32 v11, v11, v11
	ds_write_b16 v2, v11 offset:880
	v_mul_f32_e32 v12, v84, v212
	v_cvt_pk_bf16_f32 v12, v12, v12
	ds_write_b16 v2, v12 offset:2240
	v_mul_f32_e32 v13, v85, v213
	v_cvt_pk_bf16_f32 v13, v13, v13
	ds_write_b16 v2, v13 offset:2512
	v_mul_f32_e32 v14, v86, v214
	v_cvt_pk_bf16_f32 v14, v14, v14
	ds_write_b16 v2, v14 offset:2784
	v_mul_f32_e32 v15, v87, v215
	v_cvt_pk_bf16_f32 v15, v15, v15
	ds_write_b16 v2, v15 offset:3056
	v_mul_f32_e32 v8, v88, v216
	v_cvt_pk_bf16_f32 v8, v8, v8
	ds_write_b16 v2, v8 offset:4416
	v_mul_f32_e32 v9, v89, v217
	v_cvt_pk_bf16_f32 v9, v9, v9
	ds_write_b16 v2, v9 offset:4688
	v_mul_f32_e32 v10, v90, v218
	v_cvt_pk_bf16_f32 v10, v10, v10
	ds_write_b16 v2, v10 offset:4960
	v_mul_f32_e32 v11, v91, v219
	v_cvt_pk_bf16_f32 v11, v11, v11
	ds_write_b16 v2, v11 offset:5232
	v_mul_f32_e32 v12, v92, v220
	v_cvt_pk_bf16_f32 v12, v12, v12
	ds_write_b16 v2, v12 offset:6592
	v_mul_f32_e32 v13, v93, v221
	v_cvt_pk_bf16_f32 v13, v13, v13
	ds_write_b16 v2, v13 offset:6864
	v_mul_f32_e32 v14, v94, v222
	v_cvt_pk_bf16_f32 v14, v14, v14
	ds_write_b16 v2, v14 offset:7136
	v_mul_f32_e32 v15, v95, v223
	v_cvt_pk_bf16_f32 v15, v15, v15
	ds_write_b16 v2, v15 offset:7408
	v_mul_f32_e32 v8, v48, v208
	v_cvt_pk_bf16_f32 v8, v8, v8
	ds_write_b16 v2, v8 offset:128
	v_mul_f32_e32 v9, v49, v209
	v_cvt_pk_bf16_f32 v9, v9, v9
	ds_write_b16 v2, v9 offset:400
	v_mul_f32_e32 v10, v50, v210
	v_cvt_pk_bf16_f32 v10, v10, v10
	ds_write_b16 v2, v10 offset:672
	v_mul_f32_e32 v11, v51, v211
	v_cvt_pk_bf16_f32 v11, v11, v11
	ds_write_b16 v2, v11 offset:944
	v_mul_f32_e32 v12, v52, v212
	v_cvt_pk_bf16_f32 v12, v12, v12
	ds_write_b16 v2, v12 offset:2304
	v_mul_f32_e32 v13, v53, v213
	v_cvt_pk_bf16_f32 v13, v13, v13
	ds_write_b16 v2, v13 offset:2576
	v_mul_f32_e32 v14, v54, v214
	v_cvt_pk_bf16_f32 v14, v14, v14
	ds_write_b16 v2, v14 offset:2848
	v_mul_f32_e32 v15, v55, v215
	v_cvt_pk_bf16_f32 v15, v15, v15
	ds_write_b16 v2, v15 offset:3120
	v_mul_f32_e32 v8, v56, v216
	v_cvt_pk_bf16_f32 v8, v8, v8
	ds_write_b16 v2, v8 offset:4480
	v_mul_f32_e32 v9, v57, v217
	v_cvt_pk_bf16_f32 v9, v9, v9
; __device__ __forceinline__ unsigned cvtpk(float lo, float hi) { unsigned r; asm volatile("v_cvt_pk_bf16_f32 %0, %1, %2" : "=v"(r) : "v"(lo), "v"(hi)); return r; }
; __device__ __forceinline__ float xor1_(float v) { return __int_as_float(__builtin_amdgcn_update_dpp(0, __float_as_int(v), 0xB1, 0xf, 0xf, false)); }
; __device__ __forceinline__ int crow(int r, int hi) { return (r & 3) + 8 * (r >> 2) + 4 * hi; }
; __device__ __forceinline__ void attn_block3(const BlockRef& cur, char* lds, const int wid) {
;     ...
;     for (int r = 0; r < 16; ++r) { const int orow = crow(r, hi); const float rli = __builtin_amdgcn_rcpf(li_l[orow]);
;         const size_t ro = (size_t)(wid * QBLK + orow) * D;
; #pragma unroll
;         for (int d0 = 0; d0 < 4; ++d0) { const float v = o[d0][r] * rli, v2 = o2[d0][r] * rli; const float vn = xor1_(v), vn2 = xor1_(v2);
;             if ((r32 & 1) == 0) { __builtin_nontemporal_store(cvtpk(v, vn), (unsigned*)(cur.O + ro + d0 * 32 + r32)); __builtin_nontemporal_store(cvtpk(v2, vn2), (unsigned*)(cur.O2 + ro + d0 * 32 + r32)); } } }
	ds_write_b16 v2, v9 offset:4752
	v_mul_f32_e32 v10, v58, v218
	v_cvt_pk_bf16_f32 v10, v10, v10
	ds_write_b16 v2, v10 offset:5024
	v_mul_f32_e32 v11, v59, v219
	v_cvt_pk_bf16_f32 v11, v11, v11
	ds_write_b16 v2, v11 offset:5296
	v_mul_f32_e32 v12, v60, v220
	v_cvt_pk_bf16_f32 v12, v12, v12
	ds_write_b16 v2, v12 offset:6656
	v_mul_f32_e32 v13, v61, v221
	v_cvt_pk_bf16_f32 v13, v13, v13
	ds_write_b16 v2, v13 offset:6928
	v_mul_f32_e32 v14, v62, v222
	v_cvt_pk_bf16_f32 v14, v14, v14
	ds_write_b16 v2, v14 offset:7200
	v_mul_f32_e32 v15, v63, v223
	v_cvt_pk_bf16_f32 v15, v15, v15
	ds_write_b16 v2, v15 offset:7472
	v_mul_f32_e32 v8, v16, v208
	v_cvt_pk_bf16_f32 v8, v8, v8
	ds_write_b16 v2, v8 offset:192
	v_mul_f32_e32 v9, v17, v209
	v_cvt_pk_bf16_f32 v9, v9, v9
	ds_write_b16 v2, v9 offset:464
	v_mul_f32_e32 v10, v18, v210
	v_cvt_pk_bf16_f32 v10, v10, v10
	ds_write_b16 v2, v10 offset:736
	v_mul_f32_e32 v11, v19, v211
	v_cvt_pk_bf16_f32 v11, v11, v11
	ds_write_b16 v2, v11 offset:1008
	v_mul_f32_e32 v12, v20, v212
	v_cvt_pk_bf16_f32 v12, v12, v12
	ds_write_b16 v2, v12 offset:2368
	v_mul_f32_e32 v13, v21, v213
	v_cvt_pk_bf16_f32 v13, v13, v13
	ds_write_b16 v2, v13 offset:2640
	v_mul_f32_e32 v14, v22, v214
	v_cvt_pk_bf16_f32 v14, v14, v14
	ds_write_b16 v2, v14 offset:2912
	v_mul_f32_e32 v15, v23, v215
	v_cvt_pk_bf16_f32 v15, v15, v15
	ds_write_b16 v2, v15 offset:3184
	v_mul_f32_e32 v8, v24, v216
	v_cvt_pk_bf16_f32 v8, v8, v8
	ds_write_b16 v2, v8 offset:4544
	v_mul_f32_e32 v9, v25, v217
	v_cvt_pk_bf16_f32 v9, v9, v9
	ds_write_b16 v2, v9 offset:4816
	v_mul_f32_e32 v10, v26, v218
	v_cvt_pk_bf16_f32 v10, v10, v10
	ds_write_b16 v2, v10 offset:5088
	v_mul_f32_e32 v11, v27, v219
	v_cvt_pk_bf16_f32 v11, v11, v11
	ds_write_b16 v2, v11 offset:5360
	v_mul_f32_e32 v12, v28, v220
	v_cvt_pk_bf16_f32 v12, v12, v12
	ds_write_b16 v2, v12 offset:6720
	v_mul_f32_e32 v13, v29, v221
	v_cvt_pk_bf16_f32 v13, v13, v13
	ds_write_b16 v2, v13 offset:6992
	v_mul_f32_e32 v14, v30, v222
	v_cvt_pk_bf16_f32 v14, v14, v14
	ds_write_b16 v2, v14 offset:7264
	v_mul_f32_e32 v15, v31, v223
	v_cvt_pk_bf16_f32 v15, v15, v15
	ds_write_b16 v2, v15 offset:7536
	ds_read_b128 v[144:147], v4
	ds_read_b128 v[148:151], v4 offset:1088
	ds_read_b128 v[152:155], v4 offset:2176
	ds_read_b128 v[156:159], v4 offset:3264
	ds_read_b128 v[160:163], v4 offset:4352
	ds_read_b128 v[164:167], v4 offset:5440
	ds_read_b128 v[168:171], v4 offset:6528
	ds_read_b128 v[172:175], v4 offset:7616
	s_waitcnt lgkmcnt(7)
	global_store_dwordx4 v3, v[144:147], s[4:5] nt
	s_waitcnt lgkmcnt(6)
	global_store_dwordx4 v3, v[148:151], s[4:5] offset:1024 nt
	s_waitcnt lgkmcnt(5)
	global_store_dwordx4 v3, v[152:155], s[4:5] offset:2048 nt
	s_waitcnt lgkmcnt(4)
	global_store_dwordx4 v3, v[156:159], s[4:5] offset:3072 nt
	s_waitcnt lgkmcnt(3)
	global_store_dwordx4 v5, v[160:163], s[4:5] nt
	s_waitcnt lgkmcnt(2)
	global_store_dwordx4 v5, v[164:167], s[4:5] offset:1024 nt
	s_waitcnt lgkmcnt(1)
	global_store_dwordx4 v5, v[168:171], s[4:5] offset:2048 nt
	s_waitcnt lgkmcnt(0)
	global_store_dwordx4 v5, v[172:175], s[4:5] offset:3072 nt
	v_mul_f32_e32 v8, v128, v208
	v_cvt_pk_bf16_f32 v8, v8, v8
	ds_write_b16 v2, v8
	v_mul_f32_e32 v9, v129, v209
	v_cvt_pk_bf16_f32 v9, v9, v9
	ds_write_b16 v2, v9 offset:272
	v_mul_f32_e32 v10, v130, v210
	v_cvt_pk_bf16_f32 v10, v10, v10
	ds_write_b16 v2, v10 offset:544
	v_mul_f32_e32 v11, v131, v211
	v_cvt_pk_bf16_f32 v11, v11, v11
	ds_write_b16 v2, v11 offset:816
	v_mul_f32_e32 v12, v132, v212
	v_cvt_pk_bf16_f32 v12, v12, v12
	ds_write_b16 v2, v12 offset:2176
	v_mul_f32_e32 v13, v133, v213
	v_cvt_pk_bf16_f32 v13, v13, v13
	ds_write_b16 v2, v13 offset:2448
	v_mul_f32_e32 v14, v134, v214
	v_cvt_pk_bf16_f32 v14, v14, v14
	ds_write_b16 v2, v14 offset:2720
	v_mul_f32_e32 v15, v135, v215
	v_cvt_pk_bf16_f32 v15, v15, v15
	ds_write_b16 v2, v15 offset:2992
	v_mul_f32_e32 v8, v136, v216
	v_cvt_pk_bf16_f32 v8, v8, v8
	ds_write_b16 v2, v8 offset:4352
	v_mul_f32_e32 v9, v137, v217
	v_cvt_pk_bf16_f32 v9, v9, v9
	ds_write_b16 v2, v9 offset:4624
	v_mul_f32_e32 v10, v138, v218
	v_cvt_pk_bf16_f32 v10, v10, v10
	ds_write_b16 v2, v10 offset:4896
	v_mul_f32_e32 v11, v139, v219
	v_cvt_pk_bf16_f32 v11, v11, v11
	ds_write_b16 v2, v11 offset:5168
	v_mul_f32_e32 v12, v140, v220
	v_cvt_pk_bf16_f32 v12, v12, v12
	ds_write_b16 v2, v12 offset:6528
	v_mul_f32_e32 v13, v141, v221
	v_cvt_pk_bf16_f32 v13, v13, v13
	ds_write_b16 v2, v13 offset:6800
	v_mul_f32_e32 v14, v142, v222
	v_cvt_pk_bf16_f32 v14, v14, v14
	ds_write_b16 v2, v14 offset:7072
	v_mul_f32_e32 v15, v143, v223
	v_cvt_pk_bf16_f32 v15, v15, v15
	ds_write_b16 v2, v15 offset:7344
	v_mul_f32_e32 v8, v96, v208
	v_cvt_pk_bf16_f32 v8, v8, v8
	ds_write_b16 v2, v8 offset:64
	v_mul_f32_e32 v9, v97, v209
	v_cvt_pk_bf16_f32 v9, v9, v9
	ds_write_b16 v2, v9 offset:336
	v_mul_f32_e32 v10, v98, v210
	v_cvt_pk_bf16_f32 v10, v10, v10
	ds_write_b16 v2, v10 offset:608
	v_mul_f32_e32 v11, v99, v211
	v_cvt_pk_bf16_f32 v11, v11, v11
	ds_write_b16 v2, v11 offset:880
	v_mul_f32_e32 v12, v100, v212
	v_cvt_pk_bf16_f32 v12, v12, v12
	ds_write_b16 v2, v12 offset:2240
; __device__ __forceinline__ unsigned cvtpk(float lo, float hi) { unsigned r; asm volatile("v_cvt_pk_bf16_f32 %0, %1, %2" : "=v"(r) : "v"(lo), "v"(hi)); return r; }
; __device__ __forceinline__ float xor1_(float v) { return __int_as_float(__builtin_amdgcn_update_dpp(0, __float_as_int(v), 0xB1, 0xf, 0xf, false)); }
; __device__ __forceinline__ int crow(int r, int hi) { return (r & 3) + 8 * (r >> 2) + 4 * hi; }
; __device__ __forceinline__ void attn_block3(const BlockRef& cur, char* lds, const int wid) {
;     ...
;     for (int r = 0; r < 16; ++r) { const int orow = crow(r, hi); const float rli = __builtin_amdgcn_rcpf(li_l[orow]);
;         const size_t ro = (size_t)(wid * QBLK + orow) * D;
; #pragma unroll
;         for (int d0 = 0; d0 < 4; ++d0) { const float v = o[d0][r] * rli, v2 = o2[d0][r] * rli; const float vn = xor1_(v), vn2 = xor1_(v2);
;             if ((r32 & 1) == 0) { __builtin_nontemporal_store(cvtpk(v, vn), (unsigned*)(cur.O + ro + d0 * 32 + r32)); __builtin_nontemporal_store(cvtpk(v2, vn2), (unsigned*)(cur.O2 + ro + d0 * 32 + r32)); } } }
	v_mul_f32_e32 v13, v101, v213
	v_cvt_pk_bf16_f32 v13, v13, v13
	ds_write_b16 v2, v13 offset:2512
	v_mul_f32_e32 v14, v102, v214
	v_cvt_pk_bf16_f32 v14, v14, v14
	ds_write_b16 v2, v14 offset:2784
	v_mul_f32_e32 v15, v103, v215
	v_cvt_pk_bf16_f32 v15, v15, v15
	ds_write_b16 v2, v15 offset:3056
	v_mul_f32_e32 v8, v104, v216
	v_cvt_pk_bf16_f32 v8, v8, v8
	ds_write_b16 v2, v8 offset:4416
	v_mul_f32_e32 v9, v105, v217
	v_cvt_pk_bf16_f32 v9, v9, v9
	ds_write_b16 v2, v9 offset:4688
	v_mul_f32_e32 v10, v106, v218
	v_cvt_pk_bf16_f32 v10, v10, v10
	ds_write_b16 v2, v10 offset:4960
	v_mul_f32_e32 v11, v107, v219
	v_cvt_pk_bf16_f32 v11, v11, v11
	ds_write_b16 v2, v11 offset:5232
	v_mul_f32_e32 v12, v108, v220
	v_cvt_pk_bf16_f32 v12, v12, v12
	ds_write_b16 v2, v12 offset:6592
	v_mul_f32_e32 v13, v109, v221
	v_cvt_pk_bf16_f32 v13, v13, v13
	ds_write_b16 v2, v13 offset:6864
	v_mul_f32_e32 v14, v110, v222
	v_cvt_pk_bf16_f32 v14, v14, v14
	ds_write_b16 v2, v14 offset:7136
	v_mul_f32_e32 v15, v111, v223
	v_cvt_pk_bf16_f32 v15, v15, v15
	ds_write_b16 v2, v15 offset:7408
	v_mul_f32_e32 v8, v64, v208
	v_cvt_pk_bf16_f32 v8, v8, v8
	ds_write_b16 v2, v8 offset:128
	v_mul_f32_e32 v9, v65, v209
	v_cvt_pk_bf16_f32 v9, v9, v9
	ds_write_b16 v2, v9 offset:400
	v_mul_f32_e32 v10, v66, v210
	v_cvt_pk_bf16_f32 v10, v10, v10
	ds_write_b16 v2, v10 offset:672
	v_mul_f32_e32 v11, v67, v211
	v_cvt_pk_bf16_f32 v11, v11, v11
	ds_write_b16 v2, v11 offset:944
	v_mul_f32_e32 v12, v68, v212
	v_cvt_pk_bf16_f32 v12, v12, v12
	ds_write_b16 v2, v12 offset:2304
	v_mul_f32_e32 v13, v69, v213
	v_cvt_pk_bf16_f32 v13, v13, v13
	ds_write_b16 v2, v13 offset:2576
	v_mul_f32_e32 v14, v70, v214
	v_cvt_pk_bf16_f32 v14, v14, v14
	ds_write_b16 v2, v14 offset:2848
	v_mul_f32_e32 v15, v71, v215
	v_cvt_pk_bf16_f32 v15, v15, v15
	ds_write_b16 v2, v15 offset:3120
	v_mul_f32_e32 v8, v72, v216
	v_cvt_pk_bf16_f32 v8, v8, v8
	ds_write_b16 v2, v8 offset:4480
	v_mul_f32_e32 v9, v73, v217
	v_cvt_pk_bf16_f32 v9, v9, v9
	ds_write_b16 v2, v9 offset:4752
	v_mul_f32_e32 v10, v74, v218
	v_cvt_pk_bf16_f32 v10, v10, v10
	ds_write_b16 v2, v10 offset:5024
	v_mul_f32_e32 v11, v75, v219
	v_cvt_pk_bf16_f32 v11, v11, v11
	ds_write_b16 v2, v11 offset:5296
	v_mul_f32_e32 v12, v76, v220
	v_cvt_pk_bf16_f32 v12, v12, v12
	ds_write_b16 v2, v12 offset:6656
	v_mul_f32_e32 v13, v77, v221
	v_cvt_pk_bf16_f32 v13, v13, v13
	ds_write_b16 v2, v13 offset:6928
	v_mul_f32_e32 v14, v78, v222
	v_cvt_pk_bf16_f32 v14, v14, v14
	ds_write_b16 v2, v14 offset:7200
	v_mul_f32_e32 v15, v79, v223
	v_cvt_pk_bf16_f32 v15, v15, v15
	ds_write_b16 v2, v15 offset:7472
	v_mul_f32_e32 v8, v32, v208
	v_cvt_pk_bf16_f32 v8, v8, v8
	ds_write_b16 v2, v8 offset:192
	v_mul_f32_e32 v9, v33, v209
	v_cvt_pk_bf16_f32 v9, v9, v9
	ds_write_b16 v2, v9 offset:464
	v_mul_f32_e32 v10, v34, v210
	v_cvt_pk_bf16_f32 v10, v10, v10
	ds_write_b16 v2, v10 offset:736
	v_mul_f32_e32 v11, v35, v211
	v_cvt_pk_bf16_f32 v11, v11, v11
	ds_write_b16 v2, v11 offset:1008
	v_mul_f32_e32 v12, v36, v212
	v_cvt_pk_bf16_f32 v12, v12, v12
	ds_write_b16 v2, v12 offset:2368
	v_mul_f32_e32 v13, v37, v213
	v_cvt_pk_bf16_f32 v13, v13, v13
	ds_write_b16 v2, v13 offset:2640
	v_mul_f32_e32 v14, v38, v214
	v_cvt_pk_bf16_f32 v14, v14, v14
	ds_write_b16 v2, v14 offset:2912
	v_mul_f32_e32 v15, v39, v215
	v_cvt_pk_bf16_f32 v15, v15, v15
	ds_write_b16 v2, v15 offset:3184
	v_mul_f32_e32 v8, v40, v216
	v_cvt_pk_bf16_f32 v8, v8, v8
	ds_write_b16 v2, v8 offset:4544
	v_mul_f32_e32 v9, v41, v217
	v_cvt_pk_bf16_f32 v9, v9, v9
	ds_write_b16 v2, v9 offset:4816
	v_mul_f32_e32 v10, v42, v218
	v_cvt_pk_bf16_f32 v10, v10, v10
	ds_write_b16 v2, v10 offset:5088
	v_mul_f32_e32 v11, v43, v219
	v_cvt_pk_bf16_f32 v11, v11, v11
	ds_write_b16 v2, v11 offset:5360
	v_mul_f32_e32 v12, v44, v220
	v_cvt_pk_bf16_f32 v12, v12, v12
	ds_write_b16 v2, v12 offset:6720
	v_mul_f32_e32 v13, v45, v221
	v_cvt_pk_bf16_f32 v13, v13, v13
	ds_write_b16 v2, v13 offset:6992
	v_mul_f32_e32 v14, v46, v222
	v_cvt_pk_bf16_f32 v14, v14, v14
	ds_write_b16 v2, v14 offset:7264
	v_mul_f32_e32 v15, v47, v223
	v_cvt_pk_bf16_f32 v15, v15, v15
	ds_write_b16 v2, v15 offset:7536
	ds_read_b128 v[176:179], v4
	ds_read_b128 v[180:183], v4 offset:1088
	ds_read_b128 v[184:187], v4 offset:2176
	ds_read_b128 v[188:191], v4 offset:3264
	ds_read_b128 v[192:195], v4 offset:4352
	ds_read_b128 v[196:199], v4 offset:5440
	ds_read_b128 v[200:203], v4 offset:6528
	ds_read_b128 v[204:207], v4 offset:7616
	s_waitcnt lgkmcnt(7)
	global_store_dwordx4 v3, v[176:179], s[6:7] nt
	s_waitcnt lgkmcnt(6)
	global_store_dwordx4 v3, v[180:183], s[6:7] offset:1024 nt
	s_waitcnt lgkmcnt(5)
	global_store_dwordx4 v3, v[184:187], s[6:7] offset:2048 nt
	s_waitcnt lgkmcnt(4)
	global_store_dwordx4 v3, v[188:191], s[6:7] offset:3072 nt
	s_waitcnt lgkmcnt(3)
	global_store_dwordx4 v5, v[192:195], s[6:7] nt
	s_waitcnt lgkmcnt(2)
	global_store_dwordx4 v5, v[196:199], s[6:7] offset:1024 nt
	s_waitcnt lgkmcnt(1)
	global_store_dwordx4 v5, v[200:203], s[6:7] offset:2048 nt
	s_waitcnt lgkmcnt(0)
	global_store_dwordx4 v5, v[204:207], s[6:7] offset:3072 nt
	s_branch .LBB0_441
